# prep rebalanced: workgroups 0..31 (which build the S5 tables) skip 31 of their 32 x->bf16 grid-stride iterations; workgroups 32..255 take them over after their own
# speedup vs baseline: 1.1700x; 1.0052x over previous
; DI unsigned pk2(float lo, float hi) { const f32x2 v = {lo, hi}; const bf16x2_t b = __builtin_convertvector(v, bf16x2_t); return __builtin_bit_cast(unsigned, b); }
; DI void prep_phase(const Params& p, char* lds) {
;     ...
;     {
;         auto conv = [&](const float* __restrict__ srcp, bf16_t* __restrict__ dstp, size_t n8) {
;             for (size_t I = (size_t)bid * NTHR + tid; I < n8; I += (size_t)nb * NTHR) {
;                 const int c8 = (int)(I & 3), row = (int)(I >> 2) & 127, kt = (int)(I >> 9) & 31, blk = (int)(I >> 14);
;                 const float* s = srcp + ((size_t)(blk * 128 + row)) * 1024 + kt * 32 + c8 * 8;
;                 const f32x4 a = *(const f32x4*)s, b = *(const f32x4*)(s + 4);
;                 *(u32x4*)(dstp + I * 8) = (u32x4){pk2(a[0], a[1]), pk2(a[2], a[3]), pk2(b[0], b[1]), pk2(b[2], b[3])};
;             }
;         };
;         conv(p.x, WS_PTR(bf16_t, OFF_XB0), (size_t)T_TOK * DM / 8);
;         conv(p.mem, WS_PTR(bf16_t, OFF_MEMB), (size_t)4096 * DM / 8);
;     }
.Lck_posted:
	s_or_b64 exec, exec, s[0:1]
	s_ashr_i32 s51, s50, 31
	v_writelane_b32 v244, s50, 36
	s_lshl_b64 s[0:1], s[50:51], 9
	v_ashrrev_i32_e32 v3, 31, v2
	v_lshl_add_u64 v[4:5], s[0:1], 0, v[2:3]
	s_mov_b64 s[0:1], 0x400000
	v_cmp_gt_u64_e32 vcc, s[0:1], v[4:5]
	v_writelane_b32 v244, s51, 37
	s_and_saveexec_b64 s[0:1], vcc
	s_cbranch_execz .LBB0_56
	v_readlane_b32 s22, v244, 14
	v_readlane_b32 s23, v244, 15
	v_readlane_b32 s6, v244, 36
	s_movk_i32 s12, 0x7f80
	v_mov_b32_e32 v11, 0
	v_mov_b32_e32 v13, 0
	s_mov_b32 s13, 0
	s_mov_b32 s16, s6
	s_mov_b32 s14, 0
	s_mov_b32 s15, 32
	s_cmp_lt_u32 s6, 32
	s_cbranch_scc0 .Lcv_seg
	s_mov_b32 s14, 31
	s_mov_b32 s15, 1
.Lcv_seg:
	s_lshl_b32 s17, s14, 8
	s_add_u32 s17, s17, s16
	s_lshl_b32 s17, s17, 9
	v_add_u32_e32 v12, s17, v2
.Lcv_loop:
	v_lshrrev_b32_e32 v1, 2, v12
	v_lshrrev_b32_e32 v10, 7, v12
	v_and_b32_e32 v14, 0x7f, v1
	v_and_or_b32 v10, v10, s12, v14
	v_lshlrev_b32_e32 v10, 12, v10
	v_lshlrev_b32_e32 v16, 3, v12
	v_and_b32_e32 v16, 24, v16
	v_lshl_add_u64 v[14:15], s[52:53], 0, v[10:11]
	v_and_b32_e32 v10, 0xf80, v1
	v_lshl_add_u64 v[14:15], v[14:15], 0, v[10:11]
	v_lshlrev_b32_e32 v10, 2, v16
	v_lshl_add_u64 v[22:23], v[14:15], 0, v[10:11]
	global_load_dwordx4 v[14:17], v[22:23], off
	global_load_dwordx4 v[18:21], v[22:23], off offset:16
	v_lshl_add_u64 v[6:7], v[12:13], 4, s[22:23]
	v_add_u32_e32 v12, 0x20000, v12
	s_waitcnt vmcnt(1)
	v_cvt_pk_bf16_f32 v14, v14, v15
	v_cvt_pk_bf16_f32 v15, v16, v17
	s_waitcnt vmcnt(0)
	v_cvt_pk_bf16_f32 v16, v18, v19
	v_cvt_pk_bf16_f32 v17, v20, v21
	global_store_dwordx4 v[6:7], v[14:17], off
	s_sub_u32 s15, s15, 1
	s_cmp_lg_u32 s15, 0
	s_cbranch_scc1 .Lcv_loop
	s_cmp_lt_u32 s6, 32
	s_cbranch_scc1 .Lcv_done
	s_mul_i32 s17, s13, 224
	s_add_u32 s17, s17, s6
	s_sub_u32 s17, s17, 32
	s_add_u32 s13, s13, 1
	s_cmp_ge_u32 s17, 992
	s_cbranch_scc1 .Lcv_done
	s_lshr_b32 s14, s17, 5
	s_and_b32 s16, s17, 31
	s_mov_b32 s15, 1
	s_branch .Lcv_seg
.Lcv_done:
.LBB0_56:
	s_or_b64 exec, exec, s[0:1]
	s_mov_b64 s[0:1], 0x80000
	v_cmp_gt_u64_e32 vcc, s[0:1], v[4:5]
	s_and_saveexec_b64 s[0:1], vcc
	s_cbranch_execz .LBB0_59
	v_readlane_b32 s2, v244, 18
	v_readlane_b32 s6, v244, 36
	v_readlane_b32 s3, v244, 19
	s_mov_b32 s24, s2
	s_ashr_i32 s25, s2, 31
	v_readlane_b32 s7, v244, 37
	v_readlane_b32 s8, v244, 0
	s_lshl_b64 s[2:3], s[24:25], 9
	s_lshl_b64 s[4:5], s[6:7], 13
	v_readlane_b32 s22, v244, 14
	v_readlane_b32 s23, v244, 15
	s_add_u32 s4, s22, s4
	s_addc_u32 s5, s23, s5
	s_lshl_b64 s[6:7], s[6:7], 12
	v_lshl_add_u64 v[6:7], v[2:3], 4, s[4:5]
	v_lshl_add_u64 v[2:3], v[2:3], 3, s[6:7]
	s_mov_b32 s6, s24
	v_readlane_b32 s9, v244, 1
	v_readlane_b32 s10, v244, 2
	v_readlane_b32 s11, v244, 3
	v_readlane_b32 s12, v244, 4
	v_readlane_b32 s13, v244, 5
	v_readlane_b32 s14, v244, 6
	v_readlane_b32 s15, v244, 7
	v_readlane_b32 s16, v244, 8
	v_readlane_b32 s17, v244, 9
	v_readlane_b32 s18, v244, 10
	v_readlane_b32 s19, v244, 11
	v_readlane_b32 s20, v244, 12
	v_readlane_b32 s21, v244, 13
	s_mov_b64 s[4:5], 0x17200000
	v_writelane_b32 v244, s6, 18
	v_lshl_add_u64 v[6:7], v[6:7], 0, s[4:5]
	s_lshl_b64 s[4:5], s[24:25], 13
	v_writelane_b32 v244, s7, 19
	s_lshl_b64 s[6:7], s[24:25], 12
	s_mov_b64 s[8:9], 0
	s_movk_i32 s12, 0xf80
	v_mov_b32_e32 v9, 0
	s_mov_b64 s[10:11], 0x7ffff
